# v024_floop
# baseline (speedup 1.0000x reference)
; __device__ __forceinline__ void ssm_prep_item(const Params& p, int lg) {
;     ...
;   for (int it = tid; it < 1024 * 16; it += NTHR) {
;     int row = it >> 4, k8 = (it & 15) * 8, t = row >> 4, co = row & 15;
;     unsigned o[4];
; #pragma unroll
;     for (int c2 = 0; c2 < 4; ++c2) {
;       float v[2];
; #pragma unroll
;       for (int e = 0; e < 2; ++e) {
;         int k = k8 + 2 * c2 + e, pp = k & 63;
;         float pr = powre[pp * 68 + t + 1], pi = powim[pp * 68 + t + 1];
;         float cr = cre[co * 64 + pp], ci = cim[co * 64 + pp];
;         v[e] = (k < 64) ? (cr * pr - ci * pi) : -(cr * pi + ci * pr);
;       }
;       o[c2] = pack2(v[0], v[1]);
;     }
;     {
;       int c8 = k8 >> 3;
;       *reinterpret_cast<u32x4*>(F + ((size_t)((row >> 5) * 8 + (c8 >> 1)) * 64 + (row & 31) + 32 * (c8 & 1)) * 8) = u32x4{o[0], o[1], o[2], o[3]};
;     }
;   }
.LBB0_295:
	v_and_b32_e32 v80, 0x3000, v2
	v_bfe_u32 v81, v2, 2, 4
	v_lshl_or_b32 v80, v81, 8, v80
	v_bfe_u32 v81, v2, 10, 2
	v_lshl_or_b32 v80, v81, 6, v80
	v_and_b32_e32 v81, 3, v2
	v_lshl_or_b32 v80, v81, 4, v80
	v_bfe_u32 v81, v2, 6, 4
	v_or_b32_e32 v80, v80, v81
	v_lshlrev_b32_e32 v81, 3, v80
	v_lshlrev_b32_e32 v82, 5, v80
	v_ashrrev_i32_e32 v3, 4, v80
	v_ashrrev_i32_e32 v6, 8, v80
	v_and_b32_e32 v7, 56, v81
	v_ashrrev_i32_e32 v8, 6, v80
	v_bfe_u32 v9, v81, 4, 3
	s_movk_i32 s18, 0x3dff
	v_lshlrev_b32_e32 v12, 6, v3
	v_and_b32_e32 v5, 0x78, v81
	v_cmp_lt_i32_e32 vcc, s18, v2
	v_mad_u32_u24 v13, v7, s33, v6
	v_and_or_b32 v6, v8, -8, v9
	v_and_or_b32 v8, v12, s0, v7
	v_add_u32_e32 v11, 0x200, v2
	s_or_b64 s[10:11], vcc, s[10:11]
	v_cmp_gt_u32_e32 vcc, 64, v5
	v_lshl_add_u32 v5, v13, 2, 32
	v_ashrrev_i32_e32 v7, 31, v6
	v_lshl_add_u32 v8, v8, 2, 32
	v_and_b32_e32 v10, 32, v82
	v_and_b32_e32 v3, 31, v3
	v_mov_b32_e32 v2, v11
	v_add_u32_e32 v9, 0x4400, v5
	v_add_u32_e32 v11, 0x400, v5
	v_lshlrev_b64 v[26:27], 6, v[6:7]
	v_add_u32_e32 v18, 0xb800, v8
	v_add_u32_e32 v12, 0xa800, v8
	ds_read2_b32 v[22:23], v5 offset0:1 offset1:69
	ds_read2_b32 v[24:25], v5 offset0:137 offset1:205
	v_add_u32_e32 v5, 0x4800, v5
	ds_read2_b32 v[28:29], v9 offset0:1 offset1:69
	ds_read2_b32 v[30:31], v9 offset0:137 offset1:205
	ds_read2_b32 v[32:33], v11 offset0:17 offset1:85
	ds_read2_b32 v[34:35], v5 offset0:17 offset1:85
	ds_read2_b32 v[36:37], v11 offset0:153 offset1:221
	ds_read2_b32 v[38:39], v5 offset0:153 offset1:221
	v_or3_b32 v26, v26, v3, v10
	ds_read2_b64 v[6:9], v12 offset1:1
	ds_read2_b64 v[10:13], v12 offset0:2 offset1:3
	ds_read2_b64 v[14:17], v18 offset1:1
	ds_read2_b64 v[18:21], v18 offset0:2 offset1:3
	s_waitcnt lgkmcnt(11)
	v_mov_b32_e32 v40, v22
	v_mov_b32_e32 v43, v22
	s_waitcnt lgkmcnt(10)
	v_mov_b32_e32 v44, v24
	v_mov_b32_e32 v47, v24
	s_waitcnt lgkmcnt(9)
	v_mov_b32_e32 v41, v28
	v_mov_b32_e32 v42, v28
	v_mov_b32_e32 v28, v23
	v_mov_b32_e32 v22, v29
	s_waitcnt lgkmcnt(8)
	v_mov_b32_e32 v45, v30
	v_mov_b32_e32 v46, v30
	v_mov_b32_e32 v30, v25
	v_mov_b32_e32 v24, v31
	s_waitcnt lgkmcnt(7)
	v_mov_b32_e32 v48, v32
	s_waitcnt lgkmcnt(6)
	v_mov_b32_e32 v49, v34
	v_mov_b32_e32 v50, v34
	v_mov_b32_e32 v51, v32
	v_mov_b32_e32 v34, v33
	v_mov_b32_e32 v32, v35
	s_waitcnt lgkmcnt(3)
	v_mov_b32_e32 v56, v6
	s_waitcnt lgkmcnt(1)
	v_mov_b32_e32 v57, v14
	v_mov_b32_e32 v14, v7
	v_mov_b32_e32 v6, v8
	v_mov_b32_e32 v7, v16
	v_mov_b32_e32 v16, v9
	v_mov_b32_e32 v8, v10
	s_waitcnt lgkmcnt(0)
	v_mov_b32_e32 v9, v18
	v_mov_b32_e32 v18, v11
	v_mov_b32_e32 v52, v36
	v_mov_b32_e32 v53, v38
	v_mov_b32_e32 v54, v38
	v_mov_b32_e32 v55, v36
	v_mov_b32_e32 v38, v37
	v_mov_b32_e32 v36, v39
	v_mov_b32_e32 v10, v12
	v_mov_b32_e32 v11, v20
	v_mov_b32_e32 v20, v13
	v_pk_mul_f32 v[12:13], v[40:41], v[56:57]
	v_pk_mul_f32 v[28:29], v[28:29], v[14:15]
	v_pk_mul_f32 v[14:15], v[22:23], v[14:15]
	v_pk_mul_f32 v[22:23], v[44:45], v[6:7]
	v_pk_mul_f32 v[6:7], v[46:47], v[6:7]
	v_pk_mul_f32 v[30:31], v[30:31], v[16:17]
	v_pk_mul_f32 v[16:17], v[24:25], v[16:17]
	v_pk_mul_f32 v[24:25], v[48:49], v[8:9]
	v_pk_mul_f32 v[8:9], v[50:51], v[8:9]
	v_pk_mul_f32 v[34:35], v[34:35], v[18:19]
	v_pk_mul_f32 v[18:19], v[32:33], v[18:19]
	v_pk_mul_f32 v[40:41], v[42:43], v[56:57]
	v_pk_mul_f32 v[32:33], v[52:53], v[10:11]
	v_pk_mul_f32 v[10:11], v[54:55], v[10:11]
	v_pk_mul_f32 v[38:39], v[38:39], v[20:21]
	v_pk_mul_f32 v[20:21], v[36:37], v[20:21]
	v_sub_f32_e32 v3, v12, v13
	v_add_f32_e32 v13, v14, v15
	v_add_f32_e32 v6, v6, v7
	v_sub_f32_e32 v7, v30, v31
	v_add_f32_e32 v15, v16, v17
	v_sub_f32_e32 v16, v24, v25
	v_add_f32_e32 v8, v8, v9
	v_sub_f32_e32 v9, v34, v35
	v_add_f32_e32 v17, v18, v19
	v_add_u32_e32 v0, 0x4000, v0
	v_add_u32_e32 v1, 0x1000, v1
	v_lshl_add_u64 v[26:27], v[26:27], 4, s[6:7]
	v_add_f32_e32 v5, v40, v41
	v_sub_f32_e32 v12, v28, v29
	v_sub_f32_e32 v14, v22, v23
	v_sub_f32_e32 v18, v32, v33
	v_add_f32_e32 v10, v10, v11
	v_sub_f32_e32 v11, v38, v39
	v_add_f32_e32 v19, v20, v21
	v_cndmask_b32_e64 v7, -v15, v7, vcc
	v_cndmask_b32_e64 v8, -v8, v16, vcc
	v_cndmask_b32_e64 v9, -v17, v9, vcc
	v_cndmask_b32_e64 v3, -v5, v3, vcc
	v_cndmask_b32_e64 v5, -v13, v12, vcc
	v_cndmask_b32_e64 v12, -v6, v14, vcc
	v_cndmask_b32_e64 v10, -v10, v18, vcc
	v_cndmask_b32_e64 v11, -v19, v11, vcc
	v_cvt_pk_bf16_f32 v6, v3, v5
	v_cvt_pk_bf16_f32 v7, v12, v7
	v_cvt_pk_bf16_f32 v8, v8, v9
	v_cvt_pk_bf16_f32 v9, v10, v11
	global_store_dwordx4 v[26:27], v[6:9], off
	s_andn2_b64 exec, exec, s[10:11]
	s_cbranch_execnz .LBB0_295
